# v3 plus non-temporal loads and stores in the P0 weight conversion
# speedup vs baseline: 1.0283x; 1.0092x over previous
.LBB0_9:
	s_mul_hi_i32 s0, s49, 0x14d843bf
	s_lshr_b32 s1, s0, 31
	s_ashr_i32 s0, s0, 10
	s_add_i32 s12, s0, s1
	s_mul_i32 s0, s12, 0xffffcee0
	s_add_i32 s20, s49, s0
	s_cmpk_gt_i32 s20, 0xc1f
	s_mov_b64 s[0:1], -1
	s_cbranch_scc0 .LBB0_75
	s_cmpk_gt_u32 s20, 0x101f
	s_cbranch_scc0 .LBB0_40
	s_cmpk_gt_u32 s20, 0x261f
	s_cbranch_scc0 .LBB0_13
	v_readlane_b32 s52, v253, 41
	s_mul_i32 s1, s12, 0x2c00000
	v_readlane_b32 s64, v253, 53
	s_mul_hi_i32 s0, s12, 0x2c00000
	v_readlane_b32 s65, v253, 54
	s_add_u32 s1, s64, s1
	s_addc_u32 s13, s65, s0
	s_mul_i32 s14, s12, 0x1600000
	s_mul_hi_i32 s0, s12, 0x1600000
	s_add_u32 s16, s3, s14
	s_addc_u32 s17, s7, s0
	s_mul_i32 s0, s12, 0xffff9dc0
	s_add_i32 s0, s30, s0
	s_addk_i32 s0, 0xcc00
	s_and_b32 s18, s0, 0x1fc0
	s_add_i32 s0, s28, 0xfff98000
	s_and_b32 s0, s0, 0x7c0
	s_lshl_b32 s14, s0, 2
	s_add_u32 s14, s1, s14
	v_or_b32_e32 v4, s18, v67
	s_addc_u32 s15, s13, 0
	v_mov_b32_e32 v73, v69
	v_lshl_add_u64 v[2:3], s[14:15], 0, v[72:73]
	v_lshlrev_b32_e32 v68, 13, v4
	v_lshl_add_u64 v[62:63], v[2:3], 0, v[68:69]
	v_add_co_u32_e32 v6, vcc, s33, v62
	s_mov_b32 s1, 0x70000
	s_nop 0
	v_addc_co_u32_e32 v7, vcc, 0, v63, vcc
	v_add_co_u32_e32 v10, vcc, s34, v62
	global_load_dwordx4 v[2:5], v[62:63], off nt
	s_nop 0
	global_load_dwordx4 v[6:9], v[6:7], off nt
	v_addc_co_u32_e32 v11, vcc, 0, v63, vcc
	v_add_co_u32_e32 v14, vcc, s35, v62
	v_lshlrev_b32_e32 v68, 1, v70
	s_nop 0
	v_addc_co_u32_e32 v15, vcc, 0, v63, vcc
	v_add_co_u32_e32 v18, vcc, s36, v62
	global_load_dwordx4 v[10:13], v[10:11], off nt
	s_nop 0
	global_load_dwordx4 v[14:17], v[14:15], off nt
	v_addc_co_u32_e32 v19, vcc, 0, v63, vcc
	v_add_co_u32_e32 v22, vcc, s37, v62
	v_readlane_b32 s53, v253, 42
	s_nop 0
	v_addc_co_u32_e32 v23, vcc, 0, v63, vcc
	v_add_co_u32_e32 v26, vcc, s38, v62
	global_load_dwordx4 v[18:21], v[18:19], off nt
	s_nop 0
	global_load_dwordx4 v[22:25], v[22:23], off nt
	v_addc_co_u32_e32 v27, vcc, 0, v63, vcc
	v_add_co_u32_e32 v30, vcc, s39, v62
	v_readlane_b32 s54, v253, 43
	s_nop 0
	v_addc_co_u32_e32 v31, vcc, 0, v63, vcc
	v_add_co_u32_e32 v34, vcc, s40, v62
	global_load_dwordx4 v[26:29], v[26:27], off nt
	s_nop 0
	global_load_dwordx4 v[30:33], v[30:31], off nt
	v_addc_co_u32_e32 v35, vcc, 0, v63, vcc
	v_add_co_u32_e32 v38, vcc, s41, v62
	v_readlane_b32 s55, v253, 44
	s_nop 0
	v_addc_co_u32_e32 v39, vcc, 0, v63, vcc
	v_add_co_u32_e32 v42, vcc, s42, v62
	global_load_dwordx4 v[34:37], v[34:35], off nt
	s_nop 0
	global_load_dwordx4 v[38:41], v[38:39], off nt
	v_addc_co_u32_e32 v43, vcc, 0, v63, vcc
	v_add_co_u32_e32 v46, vcc, s43, v62
	v_readlane_b32 s56, v253, 45
	s_nop 0
	v_addc_co_u32_e32 v47, vcc, 0, v63, vcc
	v_add_co_u32_e32 v50, vcc, s44, v62
	global_load_dwordx4 v[42:45], v[42:43], off nt
	s_nop 0
	global_load_dwordx4 v[46:49], v[46:47], off nt
	v_addc_co_u32_e32 v51, vcc, 0, v63, vcc
	v_add_co_u32_e32 v54, vcc, s45, v62
	v_readlane_b32 s57, v253, 46
	s_nop 0
	v_addc_co_u32_e32 v55, vcc, 0, v63, vcc
	v_add_co_u32_e32 v58, vcc, s1, v62
	s_mov_b32 s1, 0x78000
	s_nop 0
	v_addc_co_u32_e32 v59, vcc, 0, v63, vcc
	v_add_co_u32_e32 v62, vcc, s1, v62
	global_load_dwordx4 v[50:53], v[50:51], off nt
	s_nop 0
	global_load_dwordx4 v[54:57], v[54:55], off nt
	v_addc_co_u32_e32 v63, vcc, 0, v63, vcc
	global_load_dwordx4 v[58:61], v[58:59], off nt
	s_lshl_b32 s1, s18, 1
	global_load_dwordx4 v[62:65], v[62:63], off nt
	s_add_u32 s14, s16, s1
	s_addc_u32 s15, s17, 0
	v_readlane_b32 s58, v253, 47
	v_readlane_b32 s59, v253, 48
	v_readlane_b32 s60, v253, 49
	v_readlane_b32 s61, v253, 50
	v_readlane_b32 s62, v253, 51
	v_readlane_b32 s63, v253, 52
	v_readlane_b32 s66, v253, 55
	v_readlane_b32 s67, v253, 56
	s_waitcnt vmcnt(15)
	ds_write2_b32 v97, v2, v3 offset1:1
	ds_write2_b32 v97, v4, v5 offset0:2 offset1:3
	s_waitcnt vmcnt(14)
	ds_write2_b32 v98, v6, v7 offset1:1
	ds_write2_b32 v99, v8, v9 offset1:1
	s_waitcnt vmcnt(13)
	ds_write2_b32 v100, v10, v11 offset1:1
	ds_write2_b32 v101, v12, v13 offset1:1
	s_waitcnt vmcnt(12)
	ds_write2_b32 v102, v14, v15 offset1:1
	ds_write2_b32 v103, v16, v17 offset1:1
	s_waitcnt vmcnt(11)
	ds_write2_b32 v104, v18, v19 offset1:1
	ds_write2_b32 v105, v20, v21 offset1:1
	s_waitcnt vmcnt(10)
	ds_write2_b32 v106, v22, v23 offset1:1
	ds_write2_b32 v107, v24, v25 offset1:1
	s_waitcnt vmcnt(9)
	ds_write2_b32 v108, v26, v27 offset1:1
	ds_write2_b32 v109, v28, v29 offset1:1
	s_waitcnt vmcnt(8)
	ds_write2_b32 v110, v30, v31 offset1:1
	ds_write2_b32 v111, v32, v33 offset1:1
	s_waitcnt vmcnt(7)
	ds_write2_b32 v112, v34, v35 offset1:1
	ds_write2_b32 v113, v36, v37 offset1:1
	s_waitcnt vmcnt(6)
	ds_write2_b32 v114, v38, v39 offset1:1
	ds_write2_b32 v115, v40, v41 offset1:1
	s_waitcnt vmcnt(5)
	ds_write2_b32 v116, v42, v43 offset1:1
	ds_write2_b32 v117, v44, v45 offset1:1
	s_waitcnt vmcnt(4)
	ds_write2_b32 v118, v46, v47 offset1:1
	ds_write2_b32 v119, v48, v49 offset1:1
	s_waitcnt vmcnt(3)
	ds_write2_b32 v120, v50, v51 offset1:1
	ds_write2_b32 v121, v52, v53 offset1:1
	s_waitcnt vmcnt(2)
	ds_write2_b32 v122, v54, v55 offset1:1
	ds_write2_b32 v123, v56, v57 offset1:1
	s_waitcnt vmcnt(1)
	ds_write2_b32 v124, v58, v59 offset1:1
	ds_write2_b32 v125, v60, v61 offset1:1
	s_waitcnt vmcnt(0)
	ds_write2_b32 v126, v62, v63 offset1:1
	v_add_u32_e32 v2, 0x3cf8, v97
	v_add_u32_e32 v26, 0x400, v78
	v_lshl_add_u64 v[22:23], s[14:15], 0, v[68:69]
	ds_write2_b32 v2, v64, v65 offset1:1
	s_waitcnt lgkmcnt(0)
	ds_read2_b32 v[6:7], v78 offset0:65 offset1:73
	ds_read2_b32 v[8:9], v78 offset1:8
	ds_read2_b32 v[10:11], v78 offset0:130 offset1:138
	ds_read2_b32 v[12:13], v78 offset0:195 offset1:203
	ds_read2_b32 v[14:15], v26 offset0:4 offset1:12
	ds_read2_b32 v[16:17], v26 offset0:69 offset1:77
	ds_read2_b32 v[18:19], v26 offset0:134 offset1:142
	ds_read2_b32 v[20:21], v26 offset0:199 offset1:207
	s_waitcnt lgkmcnt(6)
	v_cvt_pk_bf16_f32 v2, v8, v6
	v_or_b32_e32 v6, s0, v77
	v_mul_u32_u24_e32 v68, 0x2c00, v6
	v_lshl_add_u64 v[24:25], v[22:23], 0, v[68:69]
	s_waitcnt lgkmcnt(4)
	v_cvt_pk_bf16_f32 v3, v10, v12
	s_waitcnt lgkmcnt(2)
	v_cvt_pk_bf16_f32 v4, v14, v16
	s_waitcnt lgkmcnt(0)
	v_cvt_pk_bf16_f32 v5, v18, v20
	global_store_dwordx4 v[24:25], v[2:5], off nt
	v_or_b32_e32 v6, s0, v79
	v_mul_u32_u24_e32 v68, 0x2c00, v6
	v_cvt_pk_bf16_f32 v2, v9, v7
	v_cvt_pk_bf16_f32 v3, v11, v13
	v_cvt_pk_bf16_f32 v4, v15, v17
	v_cvt_pk_bf16_f32 v5, v19, v21
	ds_read2_b32 v[8:9], v78 offset0:16 offset1:24
	ds_read2_b32 v[10:11], v78 offset0:81 offset1:89
	ds_read2_b32 v[12:13], v78 offset0:146 offset1:154
	ds_read2_b32 v[14:15], v78 offset0:211 offset1:219
	ds_read2_b32 v[16:17], v26 offset0:20 offset1:28
	ds_read2_b32 v[18:19], v26 offset0:85 offset1:93
	ds_read2_b32 v[20:21], v26 offset0:150 offset1:158
	ds_read2_b32 v[24:25], v26 offset0:215 offset1:223
	v_lshl_add_u64 v[6:7], v[22:23], 0, v[68:69]
	global_store_dwordx4 v[6:7], v[2:5], off nt
	v_or_b32_e32 v6, s0, v80
	v_mul_u32_u24_e32 v68, 0x2c00, v6
	v_lshl_add_u64 v[6:7], v[22:23], 0, v[68:69]
	s_waitcnt lgkmcnt(6)
	v_cvt_pk_bf16_f32 v2, v8, v10
	s_waitcnt lgkmcnt(4)
	v_cvt_pk_bf16_f32 v3, v12, v14
	s_waitcnt lgkmcnt(2)
	v_cvt_pk_bf16_f32 v4, v16, v18
	s_waitcnt lgkmcnt(0)
	v_cvt_pk_bf16_f32 v5, v20, v24
	global_store_dwordx4 v[6:7], v[2:5], off nt
	v_or_b32_e32 v6, s0, v81
	v_mul_u32_u24_e32 v68, 0x2c00, v6
	v_cvt_pk_bf16_f32 v2, v9, v11
	v_cvt_pk_bf16_f32 v3, v13, v15
	v_cvt_pk_bf16_f32 v4, v17, v19
	v_cvt_pk_bf16_f32 v5, v21, v25
	ds_read2_b32 v[8:9], v78 offset0:32 offset1:40
	ds_read2_b32 v[10:11], v78 offset0:97 offset1:105
	ds_read2_b32 v[12:13], v78 offset0:162 offset1:170
	ds_read2_b32 v[14:15], v78 offset0:227 offset1:235
	ds_read2_b32 v[16:17], v26 offset0:36 offset1:44
	ds_read2_b32 v[18:19], v26 offset0:101 offset1:109
	ds_read2_b32 v[20:21], v26 offset0:166 offset1:174
	ds_read2_b32 v[24:25], v26 offset0:231 offset1:239
	v_lshl_add_u64 v[6:7], v[22:23], 0, v[68:69]
	global_store_dwordx4 v[6:7], v[2:5], off nt
	v_or_b32_e32 v6, s0, v82
	v_mul_u32_u24_e32 v68, 0x2c00, v6
	v_lshl_add_u64 v[6:7], v[22:23], 0, v[68:69]
	s_waitcnt lgkmcnt(6)
	v_cvt_pk_bf16_f32 v2, v8, v10
	s_waitcnt lgkmcnt(4)
	v_cvt_pk_bf16_f32 v3, v12, v14
	s_waitcnt lgkmcnt(2)
	v_cvt_pk_bf16_f32 v4, v16, v18
	s_waitcnt lgkmcnt(0)
	v_cvt_pk_bf16_f32 v5, v20, v24
	global_store_dwordx4 v[6:7], v[2:5], off nt
	v_or_b32_e32 v6, s0, v83
	v_mul_u32_u24_e32 v68, 0x2c00, v6
	v_cvt_pk_bf16_f32 v2, v9, v11
	v_cvt_pk_bf16_f32 v3, v13, v15
	v_cvt_pk_bf16_f32 v4, v17, v19
	v_cvt_pk_bf16_f32 v5, v21, v25
	ds_read2_b32 v[8:9], v78 offset0:48 offset1:56
	ds_read2_b32 v[10:11], v78 offset0:113 offset1:121
	ds_read2_b32 v[12:13], v78 offset0:178 offset1:186
	ds_read2_b32 v[14:15], v78 offset0:243 offset1:251
	ds_read2_b32 v[16:17], v26 offset0:52 offset1:60
	ds_read2_b32 v[18:19], v26 offset0:117 offset1:125
	ds_read2_b32 v[20:21], v26 offset0:182 offset1:190
	ds_read2_b32 v[24:25], v26 offset0:247 offset1:255
	v_lshl_add_u64 v[6:7], v[22:23], 0, v[68:69]
	global_store_dwordx4 v[6:7], v[2:5], off nt
	v_or_b32_e32 v6, s0, v84
	v_mul_u32_u24_e32 v68, 0x2c00, v6
	v_lshl_add_u64 v[6:7], v[22:23], 0, v[68:69]
	s_waitcnt lgkmcnt(6)
	v_cvt_pk_bf16_f32 v2, v8, v10
	s_waitcnt lgkmcnt(4)
	v_cvt_pk_bf16_f32 v3, v12, v14
	s_waitcnt lgkmcnt(2)
	v_cvt_pk_bf16_f32 v4, v16, v18
	s_waitcnt lgkmcnt(0)
	v_cvt_pk_bf16_f32 v5, v20, v24
	global_store_dwordx4 v[6:7], v[2:5], off nt
	v_or_b32_e32 v6, s0, v85
	v_mul_u32_u24_e32 v68, 0x2c00, v6
	v_lshl_add_u64 v[6:7], v[22:23], 0, v[68:69]
	v_cvt_pk_bf16_f32 v2, v9, v11
	v_cvt_pk_bf16_f32 v3, v13, v15
	v_cvt_pk_bf16_f32 v4, v17, v19
	v_cvt_pk_bf16_f32 v5, v21, v25
	global_store_dwordx4 v[6:7], v[2:5], off nt
	s_waitcnt lgkmcnt(0)
	s_mov_b64 s[0:1], 0
.LBB0_13:
	s_andn2_b64 vcc, exec, s[0:1]
	s_cbranch_vccnz .LBB0_39
	v_readlane_b32 s52, v253, 41
	s_mul_i32 s1, s12, 0x5800000
	v_readlane_b32 s58, v253, 47
	s_mul_hi_i32 s0, s12, 0x5800000
	v_readlane_b32 s59, v253, 48
	s_add_u32 s16, s58, s1
	s_addc_u32 s17, s59, s0
	s_lshl_b32 s0, s12, 11
	s_ashr_i32 s1, s0, 31
	v_readlane_b32 s56, v253, 45
	s_lshl_b64 s[0:1], s[0:1], 2
	v_readlane_b32 s57, v253, 46
	s_add_u32 s14, s56, s0
	s_addc_u32 s15, s57, s1
	s_add_i32 s0, s20, 0xefe0
	s_and_b32 s1, s0, 0xffff
	s_mul_i32 s1, s1, 0xba2f
	s_lshr_b32 s1, s1, 23
	s_mul_i32 s13, s1, 0xb0
	s_sub_i32 s13, s0, s13
	s_lshl_b32 s0, s13, 8
	s_lshl_b32 s18, s1, 6
	s_and_b32 s0, s0, 0x3ff00
	s_add_u32 s0, s16, s0
	v_or_b32_e32 v74, s18, v67
	s_addc_u32 s1, s17, 0
	v_mov_b32_e32 v73, v69
	v_lshl_add_u64 v[2:3], s[0:1], 0, v[72:73]
	v_mul_u32_u24_e32 v68, 0xb000, v74
	v_lshl_add_u64 v[2:3], v[2:3], 0, v[68:69]
	s_mov_b32 s0, 0x2c000
	v_add_co_u32_e32 v4, vcc, s0, v2
	s_mov_b32 s0, 0x84000
	s_nop 0
	v_addc_co_u32_e32 v5, vcc, 0, v3, vcc
	global_load_dwordx4 v[62:65], v[2:3], off nt
	global_load_dwordx4 v[58:61], v[4:5], off nt
	v_add_co_u32_e32 v4, vcc, s43, v2
	v_cndmask_b32_e64 v68, 0, 1, s[4:5]
	s_nop 0
	v_addc_co_u32_e32 v5, vcc, 0, v3, vcc
	v_add_co_u32_e32 v6, vcc, s0, v2
	s_mov_b32 s0, 0xb0000
	s_nop 0
	v_addc_co_u32_e32 v7, vcc, 0, v3, vcc
	global_load_dwordx4 v[54:57], v[4:5], off nt
	global_load_dwordx4 v[50:53], v[6:7], off nt
	v_add_co_u32_e32 v4, vcc, s0, v2
	s_mov_b32 s0, 0xdc000
	s_nop 0
	v_addc_co_u32_e32 v5, vcc, 0, v3, vcc
	v_add_co_u32_e32 v6, vcc, s0, v2
	s_mov_b32 s0, 0x108000
	s_nop 0
	v_addc_co_u32_e32 v7, vcc, 0, v3, vcc
	global_load_dwordx4 v[46:49], v[4:5], off nt
	global_load_dwordx4 v[42:45], v[6:7], off nt
	v_add_co_u32_e32 v4, vcc, s0, v2
	s_mov_b32 s0, 0x134000
	s_nop 0
	v_addc_co_u32_e32 v5, vcc, 0, v3, vcc
	v_add_co_u32_e32 v6, vcc, s0, v2
	s_mov_b32 s0, 0x160000
	s_nop 0
	v_addc_co_u32_e32 v7, vcc, 0, v3, vcc
	global_load_dwordx4 v[38:41], v[4:5], off nt
	global_load_dwordx4 v[34:37], v[6:7], off nt
	v_add_co_u32_e32 v4, vcc, s0, v2
	s_mov_b32 s0, 0x18c000
	s_nop 0
	v_addc_co_u32_e32 v5, vcc, 0, v3, vcc
	v_add_co_u32_e32 v6, vcc, s0, v2
	s_mov_b32 s0, 0x1b8000
	s_nop 0
	v_addc_co_u32_e32 v7, vcc, 0, v3, vcc
	global_load_dwordx4 v[30:33], v[4:5], off nt
	global_load_dwordx4 v[26:29], v[6:7], off nt
	v_add_co_u32_e32 v4, vcc, s0, v2
	s_mov_b32 s0, 0x1e4000
	s_nop 0
	v_addc_co_u32_e32 v5, vcc, 0, v3, vcc
	v_add_co_u32_e32 v6, vcc, s0, v2
	s_mov_b32 s0, 0x210000
	s_nop 0
	v_addc_co_u32_e32 v7, vcc, 0, v3, vcc
	global_load_dwordx4 v[22:25], v[4:5], off nt
	global_load_dwordx4 v[18:21], v[6:7], off nt
	v_add_co_u32_e32 v4, vcc, s0, v2
	v_cmp_ne_u32_e64 s[0:1], 1, v68
	s_nop 0
	v_addc_co_u32_e32 v5, vcc, 0, v3, vcc
	v_add_co_u32_e32 v6, vcc, 0x23c000, v2
	v_add_lshl_u32 v73, v67, s18, 2
	s_nop 0
	v_addc_co_u32_e32 v7, vcc, 0, v3, vcc
	global_load_dwordx4 v[14:17], v[4:5], off nt
	global_load_dwordx4 v[10:13], v[6:7], off nt
	v_add_co_u32_e32 v4, vcc, 0x268000, v2
	v_readlane_b32 s53, v253, 42
	s_nop 0
	v_addc_co_u32_e32 v5, vcc, 0, v3, vcc
	v_add_co_u32_e32 v2, vcc, 0x294000, v2
	v_readlane_b32 s54, v253, 43
	s_nop 0
	v_addc_co_u32_e32 v3, vcc, 0, v3, vcc
	global_load_dwordx4 v[6:9], v[4:5], off nt
	s_nop 0
	global_load_dwordx4 v[2:5], v[2:3], off nt
	s_andn2_b64 vcc, exec, s[4:5]
	v_readlane_b32 s55, v253, 44
	v_readlane_b32 s60, v253, 49
	v_readlane_b32 s61, v253, 50
	v_readlane_b32 s62, v253, 51
	v_readlane_b32 s63, v253, 52
	v_readlane_b32 s64, v253, 53
	v_readlane_b32 s65, v253, 54
	v_readlane_b32 s66, v253, 55
	v_readlane_b32 s67, v253, 56
	s_cbranch_vccnz .LBB0_156
	v_lshlrev_b32_e32 v68, 2, v74
	global_load_dword v74, v68, s[14:15]
	s_nop 0
	global_load_dword v68, v73, s[14:15] offset:16
	s_waitcnt vmcnt(1)
	v_pk_mul_f32 v[142:143], v[62:63], v[74:75] op_sel_hi:[1,0]
	v_pk_mul_f32 v[74:75], v[64:65], v[74:75] op_sel_hi:[1,0]
	ds_write2_b32 v97, v142, v143 offset1:1
	ds_write2_b32 v97, v74, v75 offset0:2 offset1:3
	s_cbranch_execnz .LBB0_17

.LBB0_38:
	s_lshl_b32 s0, s13, 6
	s_mul_i32 s14, s12, 0x2c00000
	s_mul_hi_i32 s1, s12, 0x2c00000
	s_add_u32 s14, s22, s14
	s_addc_u32 s1, s23, s1
	s_and_b32 s0, 0xffff, s0
	s_lshl_b32 s15, s18, 1
	s_add_u32 s14, s14, s15
	s_addc_u32 s15, s1, 0
	s_and_b32 s1, 0xffff, s13
	s_cmpk_gt_u32 s1, 0x57
	s_waitcnt vmcnt(0)
	v_pk_mul_f32 v[2:3], v[2:3], v[10:11] op_sel_hi:[1,0]
	v_add_u32_e32 v6, 0x1040, v19
	v_lshlrev_b32_e32 v68, 1, v70
	s_cselect_b32 s13, 0xffffea00, 0
	ds_write2_b32 v6, v2, v3 offset1:1
	v_pk_mul_f32 v[2:3], v[4:5], v[10:11] op_sel_hi:[1,0]
	v_add_u32_e32 v4, 0x1048, v19
	v_lshl_add_u64 v[22:23], s[14:15], 0, v[68:69]
	s_cselect_b32 s1, 0x80, 0
	s_add_i32 s14, s13, s0
	ds_write2_b32 v4, v2, v3 offset1:1
	s_lshl_b32 s14, s14, 1
	s_waitcnt lgkmcnt(0)
	s_and_b32 s14, s14, 0xffffff00
	s_and_b32 s15, s0, 64
	v_add_u32_e32 v26, 0x400, v78
	s_or_b32 s14, s15, s14
	ds_read2_b32 v[6:7], v78 offset0:65 offset1:73
	ds_read2_b32 v[8:9], v78 offset1:8
	ds_read2_b32 v[10:11], v78 offset0:130 offset1:138
	ds_read2_b32 v[12:13], v78 offset0:195 offset1:203
	ds_read2_b32 v[14:15], v26 offset0:4 offset1:12
	ds_read2_b32 v[16:17], v26 offset0:69 offset1:77
	ds_read2_b32 v[18:19], v26 offset0:134 offset1:142
	ds_read2_b32 v[20:21], v26 offset0:199 offset1:207
	s_or_b32 s14, s14, s1
	v_or_b32_e32 v24, s14, v77
	v_ashrrev_i32_e32 v25, 31, v24
	s_waitcnt lgkmcnt(6)
	v_cvt_pk_bf16_f32 v2, v8, v6
	v_lshlrev_b64 v[24:25], 12, v[24:25]
	v_or_b32_e32 v6, s0, v79
	v_lshl_add_u64 v[24:25], v[22:23], 0, v[24:25]
	v_add_lshl_u32 v6, v6, s13, 1
	v_mov_b32_e32 v27, s0
	s_movk_i32 s14, 0x4f
	s_waitcnt lgkmcnt(4)
	v_cvt_pk_bf16_f32 v3, v10, v12
	s_waitcnt lgkmcnt(2)
	v_cvt_pk_bf16_f32 v4, v14, v16
	s_waitcnt lgkmcnt(0)
	v_cvt_pk_bf16_f32 v5, v18, v20
	global_store_dwordx4 v[24:25], v[2:5], off nt
	v_and_b32_e32 v6, 0xffffff00, v6
	s_nop 0
	v_cvt_pk_bf16_f32 v2, v9, v7
	v_bitop3_b32 v7, v79, s14, v27 bitop3:0xc8
	v_or3_b32 v6, v7, v6, s1
	v_ashrrev_i32_e32 v7, 31, v6
	v_lshlrev_b64 v[6:7], 12, v[6:7]
	v_lshl_add_u64 v[6:7], v[22:23], 0, v[6:7]
	v_cvt_pk_bf16_f32 v3, v11, v13
	v_cvt_pk_bf16_f32 v4, v15, v17
	v_cvt_pk_bf16_f32 v5, v19, v21
	ds_read2_b32 v[8:9], v78 offset0:16 offset1:24
	ds_read2_b32 v[10:11], v78 offset0:81 offset1:89
	ds_read2_b32 v[12:13], v78 offset0:146 offset1:154
	ds_read2_b32 v[14:15], v78 offset0:211 offset1:219
	ds_read2_b32 v[16:17], v26 offset0:20 offset1:28
	ds_read2_b32 v[18:19], v26 offset0:85 offset1:93
	ds_read2_b32 v[20:21], v26 offset0:150 offset1:158
	ds_read2_b32 v[24:25], v26 offset0:215 offset1:223
	global_store_dwordx4 v[6:7], v[2:5], off nt
	v_or_b32_e32 v6, s0, v80
	v_add_lshl_u32 v6, v6, s13, 1
	s_movk_i32 s14, 0x57
	v_and_b32_e32 v6, 0xffffff00, v6
	v_bitop3_b32 v7, v80, s14, v27 bitop3:0xc8
	v_or3_b32 v6, v7, v6, s1
	v_ashrrev_i32_e32 v7, 31, v6
	v_lshlrev_b64 v[6:7], 12, v[6:7]
	v_lshl_add_u64 v[6:7], v[22:23], 0, v[6:7]
	s_waitcnt lgkmcnt(6)
	v_cvt_pk_bf16_f32 v2, v8, v10
	s_waitcnt lgkmcnt(4)
	v_cvt_pk_bf16_f32 v3, v12, v14
	s_waitcnt lgkmcnt(2)
	v_cvt_pk_bf16_f32 v4, v16, v18
	s_waitcnt lgkmcnt(0)
	v_cvt_pk_bf16_f32 v5, v20, v24
	global_store_dwordx4 v[6:7], v[2:5], off nt
	v_or_b32_e32 v6, s0, v81
	v_add_lshl_u32 v6, v6, s13, 1
	s_movk_i32 s14, 0x5f
	v_and_b32_e32 v6, 0xffffff00, v6
	v_bitop3_b32 v7, v81, s14, v27 bitop3:0xc8
	v_or3_b32 v6, v7, v6, s1
	v_ashrrev_i32_e32 v7, 31, v6
	v_lshlrev_b64 v[6:7], 12, v[6:7]
	v_lshl_add_u64 v[6:7], v[22:23], 0, v[6:7]
	v_cvt_pk_bf16_f32 v2, v9, v11
	v_cvt_pk_bf16_f32 v3, v13, v15
	v_cvt_pk_bf16_f32 v4, v17, v19
	v_cvt_pk_bf16_f32 v5, v21, v25
	ds_read2_b32 v[8:9], v78 offset0:32 offset1:40
	ds_read2_b32 v[10:11], v78 offset0:97 offset1:105
	ds_read2_b32 v[12:13], v78 offset0:162 offset1:170
	ds_read2_b32 v[14:15], v78 offset0:227 offset1:235
	ds_read2_b32 v[16:17], v26 offset0:36 offset1:44
	ds_read2_b32 v[18:19], v26 offset0:101 offset1:109
	ds_read2_b32 v[20:21], v26 offset0:166 offset1:174
	ds_read2_b32 v[24:25], v26 offset0:231 offset1:239
	global_store_dwordx4 v[6:7], v[2:5], off nt
	v_or_b32_e32 v6, s0, v82
	v_add_lshl_u32 v6, v6, s13, 1
	s_movk_i32 s14, 0x67
	v_and_b32_e32 v6, 0xffffff00, v6
	v_bitop3_b32 v7, v82, s14, v27 bitop3:0xc8
	v_or3_b32 v6, v7, v6, s1
	v_ashrrev_i32_e32 v7, 31, v6
	v_lshlrev_b64 v[6:7], 12, v[6:7]
	v_lshl_add_u64 v[6:7], v[22:23], 0, v[6:7]
	s_waitcnt lgkmcnt(6)
	v_cvt_pk_bf16_f32 v2, v8, v10
	s_waitcnt lgkmcnt(4)
	v_cvt_pk_bf16_f32 v3, v12, v14
	s_waitcnt lgkmcnt(2)
	v_cvt_pk_bf16_f32 v4, v16, v18
	s_waitcnt lgkmcnt(0)
	v_cvt_pk_bf16_f32 v5, v20, v24
	global_store_dwordx4 v[6:7], v[2:5], off nt
	v_or_b32_e32 v6, s0, v83
	v_add_lshl_u32 v6, v6, s13, 1
	s_movk_i32 s14, 0x6f
	v_and_b32_e32 v6, 0xffffff00, v6
	v_bitop3_b32 v7, v83, s14, v27 bitop3:0xc8
	v_or3_b32 v6, v7, v6, s1
	v_ashrrev_i32_e32 v7, 31, v6
	v_lshlrev_b64 v[6:7], 12, v[6:7]
	v_lshl_add_u64 v[6:7], v[22:23], 0, v[6:7]
	v_cvt_pk_bf16_f32 v2, v9, v11
	v_cvt_pk_bf16_f32 v3, v13, v15
	v_cvt_pk_bf16_f32 v4, v17, v19
	v_cvt_pk_bf16_f32 v5, v21, v25
	ds_read2_b32 v[8:9], v78 offset0:48 offset1:56
	ds_read2_b32 v[10:11], v78 offset0:113 offset1:121
	ds_read2_b32 v[12:13], v78 offset0:178 offset1:186
	ds_read2_b32 v[14:15], v78 offset0:243 offset1:251
	ds_read2_b32 v[16:17], v26 offset0:52 offset1:60
	ds_read2_b32 v[18:19], v26 offset0:117 offset1:125
	ds_read2_b32 v[20:21], v26 offset0:182 offset1:190
	ds_read2_b32 v[24:25], v26 offset0:247 offset1:255
	global_store_dwordx4 v[6:7], v[2:5], off nt
	v_or_b32_e32 v6, s0, v84
	v_add_lshl_u32 v6, v6, s13, 1
	s_movk_i32 s14, 0x77
	v_and_b32_e32 v6, 0xffffff00, v6
	v_bitop3_b32 v7, v84, s14, v27 bitop3:0xc8
	v_or3_b32 v6, v7, v6, s1
	v_ashrrev_i32_e32 v7, 31, v6
	v_lshlrev_b64 v[6:7], 12, v[6:7]
	v_lshl_add_u64 v[6:7], v[22:23], 0, v[6:7]
	s_waitcnt lgkmcnt(6)
	v_cvt_pk_bf16_f32 v2, v8, v10
	s_waitcnt lgkmcnt(4)
	v_cvt_pk_bf16_f32 v3, v12, v14
	s_waitcnt lgkmcnt(2)
	v_cvt_pk_bf16_f32 v4, v16, v18
	s_waitcnt lgkmcnt(0)
	v_cvt_pk_bf16_f32 v5, v20, v24
	global_store_dwordx4 v[6:7], v[2:5], off nt
	v_or_b32_e32 v6, s0, v85
	v_add_lshl_u32 v6, v6, s13, 1
	s_movk_i32 s0, 0x7f
	v_and_b32_e32 v6, 0xffffff00, v6
	v_bitop3_b32 v7, v85, s0, v27 bitop3:0xc8
	v_or3_b32 v6, v7, v6, s1
	v_ashrrev_i32_e32 v7, 31, v6
	v_lshlrev_b64 v[6:7], 12, v[6:7]
	v_lshl_add_u64 v[6:7], v[22:23], 0, v[6:7]
	v_cvt_pk_bf16_f32 v2, v9, v11
	v_cvt_pk_bf16_f32 v3, v13, v15
	v_cvt_pk_bf16_f32 v4, v17, v19
	v_cvt_pk_bf16_f32 v5, v21, v25
	global_store_dwordx4 v[6:7], v[2:5], off nt
	s_waitcnt lgkmcnt(0)

.LBB0_40:
	s_andn2_b64 vcc, exec, s[0:1]
	s_cbranch_vccnz .LBB0_74
	s_ashr_i32 s13, s12, 31
	v_readlane_b32 s52, v253, 41
	s_lshl_b64 s[0:1], s[12:13], 24
	v_readlane_b32 s54, v253, 43
	v_readlane_b32 s55, v253, 44
	s_add_u32 s14, s54, s0
	s_addc_u32 s15, s55, s1
	s_lshl_b32 s0, s12, 10
	s_ashr_i32 s1, s0, 31
	s_lshl_b64 s[0:1], s[0:1], 2
	v_readlane_b32 s53, v253, 42
	s_add_u32 s0, s52, s0
	s_mul_i32 s16, s12, 0xffff9dc0
	s_addc_u32 s1, s53, s1
	s_add_i32 s16, s30, s16
	s_and_b32 s21, s28, 0x7c0
	s_and_b32 s50, s16, 0x7c0
	s_lshl_b32 s16, s21, 2
	s_add_u32 s14, s14, s16
	v_or_b32_e32 v74, s50, v67
	s_addc_u32 s15, s15, 0
	v_mov_b32_e32 v73, v69
	v_lshl_add_u64 v[2:3], s[14:15], 0, v[72:73]
	v_lshlrev_b32_e32 v68, 13, v74
	v_lshl_add_u64 v[2:3], v[2:3], 0, v[68:69]
	v_add_co_u32_e32 v4, vcc, s33, v2
	s_cmpk_gt_u32 s50, 0x3ff
	s_nop 0
	v_addc_co_u32_e32 v5, vcc, 0, v3, vcc
	global_load_dwordx4 v[62:65], v[2:3], off nt
	global_load_dwordx4 v[58:61], v[4:5], off nt
	v_add_co_u32_e32 v4, vcc, s34, v2
	s_cselect_b64 s[14:15], -1, 0
	s_nop 0
	v_addc_co_u32_e32 v5, vcc, 0, v3, vcc
	v_add_co_u32_e32 v6, vcc, s35, v2
	s_and_b64 s[14:15], s[8:9], s[14:15]
	s_nop 0
	v_addc_co_u32_e32 v7, vcc, 0, v3, vcc
	global_load_dwordx4 v[54:57], v[4:5], off nt
	global_load_dwordx4 v[50:53], v[6:7], off nt
	v_add_co_u32_e32 v4, vcc, s36, v2
	s_xor_b64 s[16:17], s[14:15], -1
	s_nop 0
	v_addc_co_u32_e32 v5, vcc, 0, v3, vcc
	v_add_co_u32_e32 v6, vcc, s37, v2
	v_mov_b32_e32 v68, 1.0
	s_nop 0
	v_addc_co_u32_e32 v7, vcc, 0, v3, vcc
	global_load_dwordx4 v[46:49], v[4:5], off nt
	global_load_dwordx4 v[42:45], v[6:7], off nt
	v_add_co_u32_e32 v4, vcc, s38, v2
	v_readlane_b32 s56, v253, 45
	s_nop 0
	v_addc_co_u32_e32 v5, vcc, 0, v3, vcc
	v_add_co_u32_e32 v6, vcc, s39, v2
	v_readlane_b32 s57, v253, 46
	s_nop 0
	v_addc_co_u32_e32 v7, vcc, 0, v3, vcc
	global_load_dwordx4 v[38:41], v[4:5], off nt
	global_load_dwordx4 v[34:37], v[6:7], off nt
	v_add_co_u32_e32 v4, vcc, s40, v2
	v_readlane_b32 s58, v253, 47
	s_nop 0
	v_addc_co_u32_e32 v5, vcc, 0, v3, vcc
	v_add_co_u32_e32 v6, vcc, s41, v2
	v_readlane_b32 s59, v253, 48
	s_nop 0
	v_addc_co_u32_e32 v7, vcc, 0, v3, vcc
	global_load_dwordx4 v[30:33], v[4:5], off nt
	global_load_dwordx4 v[26:29], v[6:7], off nt
	v_add_co_u32_e32 v4, vcc, s42, v2
	v_readlane_b32 s60, v253, 49
	s_nop 0
	v_addc_co_u32_e32 v5, vcc, 0, v3, vcc
	v_add_co_u32_e32 v6, vcc, s43, v2
	v_readlane_b32 s61, v253, 50
	s_nop 0
	v_addc_co_u32_e32 v7, vcc, 0, v3, vcc
	global_load_dwordx4 v[22:25], v[4:5], off nt
	global_load_dwordx4 v[18:21], v[6:7], off nt
	v_add_co_u32_e32 v4, vcc, s44, v2
	v_readlane_b32 s62, v253, 51
	s_nop 0
	v_addc_co_u32_e32 v5, vcc, 0, v3, vcc
	v_add_co_u32_e32 v6, vcc, s45, v2
	v_readlane_b32 s63, v253, 52
	s_nop 0
	v_addc_co_u32_e32 v7, vcc, 0, v3, vcc
	global_load_dwordx4 v[14:17], v[4:5], off nt
	global_load_dwordx4 v[10:13], v[6:7], off nt
	v_add_co_u32_e32 v4, vcc, 0x70000, v2
	v_readlane_b32 s64, v253, 53
	s_nop 0
	v_addc_co_u32_e32 v5, vcc, 0, v3, vcc
	v_add_co_u32_e32 v2, vcc, 0x78000, v2
	v_readlane_b32 s65, v253, 54
	s_nop 0
	v_addc_co_u32_e32 v3, vcc, 0, v3, vcc
	global_load_dwordx4 v[6:9], v[4:5], off nt
	s_nop 0
	global_load_dwordx4 v[2:5], v[2:3], off nt
	s_and_b64 vcc, exec, s[16:17]
	v_readlane_b32 s66, v253, 55
	v_readlane_b32 s67, v253, 56
	s_cbranch_vccnz .LBB0_43
	v_lshlrev_b32_e32 v68, 2, v74
	global_load_dword v68, v68, s[0:1] offset:-4096

.LBB0_73:
	s_add_i32 s14, s20, 0xfffff3e0
	s_lshl_b64 s[0:1], s[12:13], 23
	s_add_u32 s13, s24, s0
	s_waitcnt vmcnt(0)
	v_pk_mul_f32 v[2:3], v[2:3], v[14:15] op_sel_hi:[1,0]
	v_add_u32_e32 v6, 0x1040, v15
	s_addc_u32 s15, s25, s1
	ds_write2_b32 v6, v2, v3 offset1:1
	v_pk_mul_f32 v[2:3], v[4:5], v[14:15] op_sel_hi:[1,0]
	v_add_u32_e32 v4, 0x1048, v15
	ds_write2_b32 v4, v2, v3 offset1:1
	s_cmpk_lt_u32 s14, 0x200
	s_movk_i32 s0, 0x400
	s_waitcnt lgkmcnt(0)
	s_cselect_b32 s0, s0, 0xfffffc00
	s_add_i32 s0, s50, s0
	s_ashr_i32 s1, s0, 31
	ds_read2_b32 v[6:7], v78 offset0:65 offset1:73
	ds_read2_b32 v[8:9], v78 offset1:8
	ds_read2_b32 v[10:11], v78 offset0:130 offset1:138
	ds_read2_b32 v[12:13], v78 offset0:195 offset1:203
	v_add_u32_e32 v26, 0x400, v78
	s_lshl_b64 s[0:1], s[0:1], 1
	ds_read2_b32 v[14:15], v26 offset0:4 offset1:12
	ds_read2_b32 v[16:17], v26 offset0:69 offset1:77
	ds_read2_b32 v[18:19], v26 offset0:134 offset1:142
	ds_read2_b32 v[20:21], v26 offset0:199 offset1:207
	s_add_u32 s0, s13, s0
	s_addc_u32 s1, s15, s1
	v_lshlrev_b32_e32 v68, 1, v70
	s_waitcnt lgkmcnt(6)
	v_cvt_pk_bf16_f32 v2, v8, v6
	v_or_b32_e32 v6, s21, v77
	v_lshl_add_u64 v[22:23], s[0:1], 0, v[68:69]
	v_lshlrev_b32_e32 v68, 12, v6
	v_lshl_add_u64 v[24:25], v[22:23], 0, v[68:69]
	s_waitcnt lgkmcnt(4)
	v_cvt_pk_bf16_f32 v3, v10, v12
	s_waitcnt lgkmcnt(2)
	v_cvt_pk_bf16_f32 v4, v14, v16
	s_waitcnt lgkmcnt(0)
	v_cvt_pk_bf16_f32 v5, v18, v20
	global_store_dwordx4 v[24:25], v[2:5], off nt
	v_or_b32_e32 v6, s21, v79
	v_lshlrev_b32_e32 v68, 12, v6
	v_cvt_pk_bf16_f32 v2, v9, v7
	v_cvt_pk_bf16_f32 v3, v11, v13
	v_cvt_pk_bf16_f32 v4, v15, v17
	v_cvt_pk_bf16_f32 v5, v19, v21
	ds_read2_b32 v[8:9], v78 offset0:16 offset1:24
	ds_read2_b32 v[10:11], v78 offset0:81 offset1:89
	ds_read2_b32 v[12:13], v78 offset0:146 offset1:154
	ds_read2_b32 v[14:15], v78 offset0:211 offset1:219
	ds_read2_b32 v[16:17], v26 offset0:20 offset1:28
	ds_read2_b32 v[18:19], v26 offset0:85 offset1:93
	ds_read2_b32 v[20:21], v26 offset0:150 offset1:158
	ds_read2_b32 v[24:25], v26 offset0:215 offset1:223
	v_lshl_add_u64 v[6:7], v[22:23], 0, v[68:69]
	global_store_dwordx4 v[6:7], v[2:5], off nt
	v_or_b32_e32 v6, s21, v80
	v_lshlrev_b32_e32 v68, 12, v6
	v_lshl_add_u64 v[6:7], v[22:23], 0, v[68:69]
	s_waitcnt lgkmcnt(6)
	v_cvt_pk_bf16_f32 v2, v8, v10
	s_waitcnt lgkmcnt(4)
	v_cvt_pk_bf16_f32 v3, v12, v14
	s_waitcnt lgkmcnt(2)
	v_cvt_pk_bf16_f32 v4, v16, v18
	s_waitcnt lgkmcnt(0)
	v_cvt_pk_bf16_f32 v5, v20, v24
	global_store_dwordx4 v[6:7], v[2:5], off nt
	v_or_b32_e32 v6, s21, v81
	v_lshlrev_b32_e32 v68, 12, v6
	v_cvt_pk_bf16_f32 v2, v9, v11
	v_cvt_pk_bf16_f32 v3, v13, v15
	v_cvt_pk_bf16_f32 v4, v17, v19
	v_cvt_pk_bf16_f32 v5, v21, v25
	ds_read2_b32 v[8:9], v78 offset0:32 offset1:40
	ds_read2_b32 v[10:11], v78 offset0:97 offset1:105
	ds_read2_b32 v[12:13], v78 offset0:162 offset1:170
	ds_read2_b32 v[14:15], v78 offset0:227 offset1:235
	ds_read2_b32 v[16:17], v26 offset0:36 offset1:44
	ds_read2_b32 v[18:19], v26 offset0:101 offset1:109
	ds_read2_b32 v[20:21], v26 offset0:166 offset1:174
	ds_read2_b32 v[24:25], v26 offset0:231 offset1:239
	v_lshl_add_u64 v[6:7], v[22:23], 0, v[68:69]
	global_store_dwordx4 v[6:7], v[2:5], off nt
	v_or_b32_e32 v6, s21, v82
	v_lshlrev_b32_e32 v68, 12, v6
	v_lshl_add_u64 v[6:7], v[22:23], 0, v[68:69]
	s_waitcnt lgkmcnt(6)
	v_cvt_pk_bf16_f32 v2, v8, v10
	s_waitcnt lgkmcnt(4)
	v_cvt_pk_bf16_f32 v3, v12, v14
	s_waitcnt lgkmcnt(2)
	v_cvt_pk_bf16_f32 v4, v16, v18
	s_waitcnt lgkmcnt(0)
	v_cvt_pk_bf16_f32 v5, v20, v24
	global_store_dwordx4 v[6:7], v[2:5], off nt
	v_or_b32_e32 v6, s21, v83
	v_lshlrev_b32_e32 v68, 12, v6
	v_cvt_pk_bf16_f32 v2, v9, v11
	v_cvt_pk_bf16_f32 v3, v13, v15
	v_cvt_pk_bf16_f32 v4, v17, v19
	v_cvt_pk_bf16_f32 v5, v21, v25
	ds_read2_b32 v[8:9], v78 offset0:48 offset1:56
	ds_read2_b32 v[10:11], v78 offset0:113 offset1:121
	ds_read2_b32 v[12:13], v78 offset0:178 offset1:186
	ds_read2_b32 v[14:15], v78 offset0:243 offset1:251
	ds_read2_b32 v[16:17], v26 offset0:52 offset1:60
	ds_read2_b32 v[18:19], v26 offset0:117 offset1:125
	ds_read2_b32 v[20:21], v26 offset0:182 offset1:190
	ds_read2_b32 v[24:25], v26 offset0:247 offset1:255
	v_lshl_add_u64 v[6:7], v[22:23], 0, v[68:69]
	global_store_dwordx4 v[6:7], v[2:5], off nt
	v_or_b32_e32 v6, s21, v84
	v_lshlrev_b32_e32 v68, 12, v6
	v_lshl_add_u64 v[6:7], v[22:23], 0, v[68:69]
	s_waitcnt lgkmcnt(6)
	v_cvt_pk_bf16_f32 v2, v8, v10
	s_waitcnt lgkmcnt(4)
	v_cvt_pk_bf16_f32 v3, v12, v14
	s_waitcnt lgkmcnt(2)
	v_cvt_pk_bf16_f32 v4, v16, v18
	s_waitcnt lgkmcnt(0)
	v_cvt_pk_bf16_f32 v5, v20, v24
	global_store_dwordx4 v[6:7], v[2:5], off nt
	v_or_b32_e32 v6, s21, v85
	v_lshlrev_b32_e32 v68, 12, v6
	v_lshl_add_u64 v[6:7], v[22:23], 0, v[68:69]
	v_cvt_pk_bf16_f32 v2, v9, v11
	v_cvt_pk_bf16_f32 v3, v13, v15
	v_cvt_pk_bf16_f32 v4, v17, v19
	v_cvt_pk_bf16_f32 v5, v21, v25
	global_store_dwordx4 v[6:7], v[2:5], off nt
	s_waitcnt lgkmcnt(0)

.LBB0_75:
	s_andn2_b64 vcc, exec, s[0:1]
	s_cbranch_vccnz .LBB0_8
	s_mul_i32 s1, s12, 0x3020000
	v_readlane_b32 s52, v253, 25
	s_mul_hi_i32 s0, s12, 0x3020000
	v_readlane_b32 s53, v253, 26
	s_add_u32 s13, s52, s1
	s_addc_u32 s15, s53, s0
	s_mul_i32 s0, s20, 0xffffa8e9
	s_lshr_b32 s0, s0, 16
	s_add_i32 s0, s0, s20
	s_sext_i32_i16 s1, s0
	s_ashr_i32 s1, s1, 6
	s_bfe_u32 s0, s0, 0x1000f
	s_add_i32 s0, s1, s0
	s_sext_i32_i16 s1, s0
	s_mulk_i32 s0, 0x61
	s_sub_i32 s0, s20, s0
	s_sext_i32_i16 s0, s0
	s_lshl_b32 s0, s0, 6
	s_lshl_b32 s14, s1, 6
	s_ashr_i32 s1, s0, 31
	s_lshl_b64 s[16:17], s[0:1], 2
	v_or_b32_e32 v2, s0, v66
	s_add_u32 s16, s13, s16
	v_cmp_gt_i32_e32 vcc, s46, v2
	s_addc_u32 s17, s15, s17
	v_mov_b32_e32 v73, v69
	v_mov_b32_e32 v2, 0
	v_or_b32_e32 v68, s14, v67
	v_lshl_add_u64 v[74:75], s[16:17], 0, v[72:73]
	v_mov_b32_e32 v22, 0
	v_mov_b32_e32 v23, v2
	v_mov_b32_e32 v24, 0
	v_mov_b32_e32 v25, 0
	v_readlane_b32 s54, v253, 27
	v_readlane_b32 s55, v253, 28
	v_readlane_b32 s56, v253, 29
	v_readlane_b32 s57, v253, 30
	v_readlane_b32 s58, v253, 31
	v_readlane_b32 s59, v253, 32
	v_readlane_b32 s60, v253, 33
	v_readlane_b32 s61, v253, 34
	v_readlane_b32 s62, v253, 35
	v_readlane_b32 s63, v253, 36
	v_readlane_b32 s64, v253, 37
	v_readlane_b32 s65, v253, 38
	v_readlane_b32 s66, v253, 39
	v_readlane_b32 s67, v253, 40
	s_and_saveexec_b64 s[16:17], vcc
	s_cbranch_execz .LBB0_78
	v_mul_i32_i24_e32 v4, 0x6040, v68
	v_ashrrev_i32_e32 v5, 31, v4
	v_lshl_add_u64 v[4:5], v[74:75], 0, v[4:5]
	global_load_dwordx4 v[22:25], v[4:5], off nt
.LBB0_78:
	s_or_b64 exec, exec, s[16:17]
	v_mov_b32_e32 v3, 0
	v_mov_b32_e32 v4, 0
	v_mov_b32_e32 v5, 0
	s_and_saveexec_b64 s[16:17], vcc
	s_cbranch_execz .LBB0_80
	v_mad_i32_i24 v2, v68, s47, v127
	v_ashrrev_i32_e32 v3, 31, v2
	v_lshl_add_u64 v[2:3], v[74:75], 0, v[2:3]
	global_load_dwordx4 v[2:5], v[2:3], off nt
.LBB0_80:
	s_or_b64 exec, exec, s[16:17]
	v_mov_b32_e32 v6, 0
	v_mov_b32_e32 v30, 0
	v_mov_b32_e32 v31, 0
	v_mov_b32_e32 v32, 0
	v_mov_b32_e32 v33, 0
	s_and_saveexec_b64 s[16:17], vcc
	s_cbranch_execz .LBB0_82
	v_mad_i32_i24 v8, v68, s47, v128
	v_ashrrev_i32_e32 v9, 31, v8
	v_lshl_add_u64 v[8:9], v[74:75], 0, v[8:9]
	global_load_dwordx4 v[30:33], v[8:9], off nt
.LBB0_82:
	s_or_b64 exec, exec, s[16:17]
	v_mov_b32_e32 v7, 0
	v_mov_b32_e32 v8, 0
	v_mov_b32_e32 v9, 0
	s_and_saveexec_b64 s[16:17], vcc
	s_cbranch_execz .LBB0_84
	v_mad_i32_i24 v6, v68, s47, v129
	v_ashrrev_i32_e32 v7, 31, v6
	v_lshl_add_u64 v[6:7], v[74:75], 0, v[6:7]
	global_load_dwordx4 v[6:9], v[6:7], off nt
.LBB0_84:
	s_or_b64 exec, exec, s[16:17]
	v_mov_b32_e32 v10, 0
	v_mov_b32_e32 v42, 0
	v_mov_b32_e32 v43, 0
	v_mov_b32_e32 v44, 0
	v_mov_b32_e32 v45, 0
	s_and_saveexec_b64 s[16:17], vcc
	s_cbranch_execz .LBB0_86
	v_mad_i32_i24 v12, v68, s47, v130
	v_ashrrev_i32_e32 v13, 31, v12
	v_lshl_add_u64 v[12:13], v[74:75], 0, v[12:13]
	global_load_dwordx4 v[42:45], v[12:13], off nt
.LBB0_86:
	s_or_b64 exec, exec, s[16:17]
	v_mov_b32_e32 v11, 0
	v_mov_b32_e32 v12, 0
	v_mov_b32_e32 v13, 0
	s_and_saveexec_b64 s[16:17], vcc
	s_cbranch_execz .LBB0_88
	v_mad_i32_i24 v10, v68, s47, v131
	v_ashrrev_i32_e32 v11, 31, v10
	v_lshl_add_u64 v[10:11], v[74:75], 0, v[10:11]
	global_load_dwordx4 v[10:13], v[10:11], off nt
.LBB0_88:
	s_or_b64 exec, exec, s[16:17]
	v_mov_b32_e32 v14, 0
	v_mov_b32_e32 v46, 0
	v_mov_b32_e32 v47, 0
	v_mov_b32_e32 v48, 0
	v_mov_b32_e32 v49, 0
	s_and_saveexec_b64 s[16:17], vcc
	s_cbranch_execz .LBB0_90
	v_mad_i32_i24 v16, v68, s47, v132
	v_ashrrev_i32_e32 v17, 31, v16
	v_lshl_add_u64 v[16:17], v[74:75], 0, v[16:17]
	global_load_dwordx4 v[46:49], v[16:17], off nt
.LBB0_90:
	s_or_b64 exec, exec, s[16:17]
	v_mov_b32_e32 v15, 0
	v_mov_b32_e32 v16, 0
	v_mov_b32_e32 v17, 0
	s_and_saveexec_b64 s[16:17], vcc
	s_cbranch_execz .LBB0_92
	v_mad_i32_i24 v14, v68, s47, v133
	v_ashrrev_i32_e32 v15, 31, v14
	v_lshl_add_u64 v[14:15], v[74:75], 0, v[14:15]
	global_load_dwordx4 v[14:17], v[14:15], off nt
.LBB0_92:
	s_or_b64 exec, exec, s[16:17]
	v_mov_b32_e32 v18, 0
	v_mov_b32_e32 v50, 0
	v_mov_b32_e32 v51, 0
	v_mov_b32_e32 v52, 0
	v_mov_b32_e32 v53, 0
	s_and_saveexec_b64 s[16:17], vcc
	s_cbranch_execz .LBB0_94
	v_mad_i32_i24 v20, v68, s47, v134
	v_ashrrev_i32_e32 v21, 31, v20
	v_lshl_add_u64 v[20:21], v[74:75], 0, v[20:21]
	global_load_dwordx4 v[50:53], v[20:21], off nt
.LBB0_94:
	s_or_b64 exec, exec, s[16:17]
	v_mov_b32_e32 v19, 0
	v_mov_b32_e32 v20, 0
	v_mov_b32_e32 v21, 0
	s_and_saveexec_b64 s[16:17], vcc
	s_cbranch_execz .LBB0_96
	v_mad_i32_i24 v18, v68, s47, v135
	v_ashrrev_i32_e32 v19, 31, v18
	v_lshl_add_u64 v[18:19], v[74:75], 0, v[18:19]
	global_load_dwordx4 v[18:21], v[18:19], off nt
.LBB0_96:
	s_or_b64 exec, exec, s[16:17]
	v_mov_b32_e32 v26, 0
	v_mov_b32_e32 v54, 0
	v_mov_b32_e32 v55, 0
	v_mov_b32_e32 v56, 0
	v_mov_b32_e32 v57, 0
	s_and_saveexec_b64 s[16:17], vcc
	s_cbranch_execz .LBB0_98
	v_mad_i32_i24 v28, v68, s47, v136
	v_ashrrev_i32_e32 v29, 31, v28
	v_lshl_add_u64 v[28:29], v[74:75], 0, v[28:29]
	global_load_dwordx4 v[54:57], v[28:29], off nt
.LBB0_98:
	s_or_b64 exec, exec, s[16:17]
	v_mov_b32_e32 v27, 0
	v_mov_b32_e32 v28, 0
	v_mov_b32_e32 v29, 0
	s_and_saveexec_b64 s[16:17], vcc
	s_cbranch_execz .LBB0_100
	v_mad_i32_i24 v26, v68, s47, v137
	v_ashrrev_i32_e32 v27, 31, v26
	v_lshl_add_u64 v[26:27], v[74:75], 0, v[26:27]
	global_load_dwordx4 v[26:29], v[26:27], off nt
.LBB0_100:
	s_or_b64 exec, exec, s[16:17]
	v_mov_b32_e32 v34, 0
	v_mov_b32_e32 v58, 0
	v_mov_b32_e32 v59, 0
	v_mov_b32_e32 v60, 0
	v_mov_b32_e32 v61, 0
	s_and_saveexec_b64 s[16:17], vcc
	s_cbranch_execz .LBB0_102
	v_mad_i32_i24 v36, v68, s47, v138
	v_ashrrev_i32_e32 v37, 31, v36
	v_lshl_add_u64 v[36:37], v[74:75], 0, v[36:37]
	global_load_dwordx4 v[58:61], v[36:37], off nt
.LBB0_102:
	s_or_b64 exec, exec, s[16:17]
	v_mov_b32_e32 v35, 0
	v_mov_b32_e32 v36, 0
	v_mov_b32_e32 v37, 0
	s_and_saveexec_b64 s[16:17], vcc
	s_cbranch_execz .LBB0_104
	v_mad_i32_i24 v34, v68, s47, v139
	v_ashrrev_i32_e32 v35, 31, v34
	v_lshl_add_u64 v[34:35], v[74:75], 0, v[34:35]
	global_load_dwordx4 v[34:37], v[34:35], off nt
.LBB0_104:
	s_or_b64 exec, exec, s[16:17]
	v_mov_b32_e32 v38, 0
	v_mov_b32_e32 v62, 0
	v_mov_b32_e32 v63, 0
	v_mov_b32_e32 v64, 0
	v_mov_b32_e32 v65, 0
	s_and_saveexec_b64 s[16:17], vcc
	s_cbranch_execz .LBB0_106
	v_mad_i32_i24 v40, v68, s47, v140
	v_ashrrev_i32_e32 v41, 31, v40
	v_lshl_add_u64 v[40:41], v[74:75], 0, v[40:41]
	global_load_dwordx4 v[62:65], v[40:41], off nt
.LBB0_106:
	s_or_b64 exec, exec, s[16:17]
	v_mov_b32_e32 v39, 0
	v_mov_b32_e32 v40, 0
	v_mov_b32_e32 v41, 0
	s_and_saveexec_b64 s[16:17], vcc
	s_cbranch_execz .LBB0_108
	v_mad_i32_i24 v38, v68, s47, v141
	v_ashrrev_i32_e32 v39, 31, v38
	v_lshl_add_u64 v[38:39], v[74:75], 0, v[38:39]
	global_load_dwordx4 v[38:41], v[38:39], off nt

.LBB0_140:
	s_waitcnt vmcnt(0)
	v_pk_mul_f32 v[4:5], v[38:39], v[2:3] op_sel_hi:[1,0]
	v_add_u32_e32 v6, 0x1040, v3
	ds_write2_b32 v6, v4, v5 offset1:1
	v_pk_mul_f32 v[4:5], v[40:41], v[2:3] op_sel_hi:[1,0]
	v_add_u32_e32 v2, 0x1048, v3
	ds_write2_b32 v2, v4, v5 offset1:1
	s_mul_hi_i32 s1, s12, 0x1820000
	s_mul_i32 s12, s12, 0x1820000
	s_waitcnt lgkmcnt(0)
	s_add_u32 s16, s26, s12
	v_add_u32_e32 v8, 0x400, v78
	s_addc_u32 s1, s27, s1
	s_ashr_i32 s15, s14, 31
	ds_read2_b32 v[2:3], v78 offset1:65
	ds_read2_b32 v[4:5], v78 offset0:130 offset1:195
	ds_read2_b32 v[10:11], v8 offset0:4 offset1:69
	ds_read2_b32 v[12:13], v8 offset0:134 offset1:199
	s_lshl_b64 s[12:13], s[14:15], 1
	s_add_u32 s12, s16, s12
	s_addc_u32 s13, s1, s13
	v_lshlrev_b32_e32 v68, 1, v70
	v_or_b32_e32 v9, s0, v77
	v_lshl_add_u64 v[6:7], s[12:13], 0, v[68:69]
	v_cmp_gt_i32_e32 vcc, s46, v9
	s_waitcnt lgkmcnt(3)
	v_cvt_pk_bf16_f32 v2, v2, v3
	s_waitcnt lgkmcnt(2)
	v_cvt_pk_bf16_f32 v3, v4, v5
	s_waitcnt lgkmcnt(1)
	v_cvt_pk_bf16_f32 v4, v10, v11
	s_waitcnt lgkmcnt(0)
	v_cvt_pk_bf16_f32 v5, v12, v13
	s_and_saveexec_b64 s[12:13], vcc
	s_cbranch_execz .LBB0_142
	s_lshr_b32 s1, s0, 1
	s_and_b32 s1, s1, 0x60
	v_and_b32_e32 v10, 0xffffff07, v9
	v_or_b32_e32 v10, s1, v10
	v_cmp_lt_i32_e32 vcc, s48, v9
	s_nop 1
	v_cndmask_b32_e32 v10, v10, v9, vcc
	v_ashrrev_i32_e32 v11, 31, v10
	v_lshlrev_b64 v[10:11], 12, v[10:11]
	v_lshl_add_u64 v[10:11], v[6:7], 0, v[10:11]
	global_store_dwordx4 v[10:11], v[2:5], off nt
.LBB0_142:
	s_or_b64 exec, exec, s[12:13]
	ds_read2_b32 v[2:3], v78 offset0:8 offset1:73
	ds_read2_b32 v[4:5], v78 offset0:138 offset1:203
	ds_read2_b32 v[10:11], v8 offset0:12 offset1:77
	ds_read2_b32 v[12:13], v8 offset0:142 offset1:207
	v_or_b32_e32 v9, s0, v79
	v_cmp_gt_i32_e32 vcc, s46, v9
	s_waitcnt lgkmcnt(3)
	v_cvt_pk_bf16_f32 v2, v2, v3
	s_waitcnt lgkmcnt(2)
	v_cvt_pk_bf16_f32 v3, v4, v5
	s_waitcnt lgkmcnt(1)
	v_cvt_pk_bf16_f32 v4, v10, v11
	s_waitcnt lgkmcnt(0)
	v_cvt_pk_bf16_f32 v5, v12, v13
	s_and_saveexec_b64 s[12:13], vcc
	s_cbranch_execz .LBB0_144
	s_lshr_b32 s1, s0, 1
	s_and_b32 s1, s1, 0x60
	v_and_b32_e32 v10, 0xffffff0f, v9
	v_or_b32_e32 v10, s1, v10
	v_cmp_lt_i32_e32 vcc, s48, v9
	s_nop 1
	v_cndmask_b32_e32 v10, v10, v9, vcc
	v_ashrrev_i32_e32 v11, 31, v10
	v_lshlrev_b64 v[10:11], 12, v[10:11]
	v_lshl_add_u64 v[10:11], v[6:7], 0, v[10:11]
	global_store_dwordx4 v[10:11], v[2:5], off nt
.LBB0_144:
	s_or_b64 exec, exec, s[12:13]
	ds_read2_b32 v[2:3], v78 offset0:16 offset1:81
	ds_read2_b32 v[4:5], v78 offset0:146 offset1:211
	ds_read2_b32 v[10:11], v8 offset0:20 offset1:85
	ds_read2_b32 v[12:13], v8 offset0:150 offset1:215
	v_or_b32_e32 v9, s0, v80
	v_cmp_gt_i32_e32 vcc, s46, v9
	s_waitcnt lgkmcnt(3)
	v_cvt_pk_bf16_f32 v2, v2, v3
	s_waitcnt lgkmcnt(2)
	v_cvt_pk_bf16_f32 v3, v4, v5
	s_waitcnt lgkmcnt(1)
	v_cvt_pk_bf16_f32 v4, v10, v11
	s_waitcnt lgkmcnt(0)
	v_cvt_pk_bf16_f32 v5, v12, v13
	s_and_saveexec_b64 s[12:13], vcc
	s_cbranch_execz .LBB0_146
	s_lshr_b32 s1, s0, 1
	s_and_b32 s1, s1, 0x60
	v_and_b32_e32 v10, 0xffffff17, v9
	v_or_b32_e32 v10, s1, v10
	v_cmp_lt_i32_e32 vcc, s48, v9
	s_nop 1
	v_cndmask_b32_e32 v10, v10, v9, vcc
	v_ashrrev_i32_e32 v11, 31, v10
	v_lshlrev_b64 v[10:11], 12, v[10:11]
	v_lshl_add_u64 v[10:11], v[6:7], 0, v[10:11]
	global_store_dwordx4 v[10:11], v[2:5], off nt
.LBB0_146:
	s_or_b64 exec, exec, s[12:13]
	ds_read2_b32 v[2:3], v78 offset0:24 offset1:89
	ds_read2_b32 v[4:5], v78 offset0:154 offset1:219
	ds_read2_b32 v[10:11], v8 offset0:28 offset1:93
	ds_read2_b32 v[12:13], v8 offset0:158 offset1:223
	v_or_b32_e32 v9, s0, v81
	v_cmp_gt_i32_e32 vcc, s46, v9
	s_waitcnt lgkmcnt(3)
	v_cvt_pk_bf16_f32 v2, v2, v3
	s_waitcnt lgkmcnt(2)
	v_cvt_pk_bf16_f32 v3, v4, v5
	s_waitcnt lgkmcnt(1)
	v_cvt_pk_bf16_f32 v4, v10, v11
	s_waitcnt lgkmcnt(0)
	v_cvt_pk_bf16_f32 v5, v12, v13
	s_and_saveexec_b64 s[12:13], vcc
	s_cbranch_execz .LBB0_148
	s_lshr_b32 s1, s0, 1
	s_and_b32 s1, s1, 0x60
	v_and_b32_e32 v10, 0xffffff1f, v9
	v_or_b32_e32 v10, s1, v10
	v_cmp_lt_i32_e32 vcc, s48, v9
	s_nop 1
	v_cndmask_b32_e32 v10, v10, v9, vcc
	v_ashrrev_i32_e32 v11, 31, v10
	v_lshlrev_b64 v[10:11], 12, v[10:11]
	v_lshl_add_u64 v[10:11], v[6:7], 0, v[10:11]
	global_store_dwordx4 v[10:11], v[2:5], off nt
.LBB0_148:
	s_or_b64 exec, exec, s[12:13]
	ds_read2_b32 v[2:3], v78 offset0:32 offset1:97
	ds_read2_b32 v[4:5], v78 offset0:162 offset1:227
	ds_read2_b32 v[10:11], v8 offset0:36 offset1:101
	ds_read2_b32 v[12:13], v8 offset0:166 offset1:231
	v_or_b32_e32 v9, s0, v82
	v_cmp_gt_i32_e32 vcc, s46, v9
	s_waitcnt lgkmcnt(3)
	v_cvt_pk_bf16_f32 v2, v2, v3
	s_waitcnt lgkmcnt(2)
	v_cvt_pk_bf16_f32 v3, v4, v5
	s_waitcnt lgkmcnt(1)
	v_cvt_pk_bf16_f32 v4, v10, v11
	s_waitcnt lgkmcnt(0)
	v_cvt_pk_bf16_f32 v5, v12, v13
	s_and_saveexec_b64 s[12:13], vcc
	s_cbranch_execz .LBB0_150
	s_lshr_b32 s1, s0, 1
	s_and_b32 s1, s1, 0x60
	v_and_b32_e32 v10, 0xffffff07, v9
	v_or_b32_e32 v10, s1, v10
	v_or_b32_e32 v10, 0x80, v10
	v_cmp_lt_i32_e32 vcc, s48, v9
	s_nop 1
	v_cndmask_b32_e32 v10, v10, v9, vcc
	v_ashrrev_i32_e32 v11, 31, v10
	v_lshlrev_b64 v[10:11], 12, v[10:11]
	v_lshl_add_u64 v[10:11], v[6:7], 0, v[10:11]
	global_store_dwordx4 v[10:11], v[2:5], off nt
.LBB0_150:
	s_or_b64 exec, exec, s[12:13]
	ds_read2_b32 v[2:3], v78 offset0:40 offset1:105
	ds_read2_b32 v[4:5], v78 offset0:170 offset1:235
	ds_read2_b32 v[10:11], v8 offset0:44 offset1:109
	ds_read2_b32 v[12:13], v8 offset0:174 offset1:239
	v_or_b32_e32 v9, s0, v83
	v_cmp_gt_i32_e32 vcc, s46, v9
	s_waitcnt lgkmcnt(3)
	v_cvt_pk_bf16_f32 v2, v2, v3
	s_waitcnt lgkmcnt(2)
	v_cvt_pk_bf16_f32 v3, v4, v5
	s_waitcnt lgkmcnt(1)
	v_cvt_pk_bf16_f32 v4, v10, v11
	s_waitcnt lgkmcnt(0)
	v_cvt_pk_bf16_f32 v5, v12, v13
	s_and_saveexec_b64 s[12:13], vcc
	s_cbranch_execz .LBB0_152
	s_lshr_b32 s1, s0, 1
	s_and_b32 s1, s1, 0x60
	v_and_b32_e32 v10, 0xffffff0f, v9
	v_or_b32_e32 v10, s1, v10
	v_or_b32_e32 v10, 0x80, v10
	v_cmp_lt_i32_e32 vcc, s48, v9
	s_nop 1
	v_cndmask_b32_e32 v10, v10, v9, vcc
	v_ashrrev_i32_e32 v11, 31, v10
	v_lshlrev_b64 v[10:11], 12, v[10:11]
	v_lshl_add_u64 v[10:11], v[6:7], 0, v[10:11]
	global_store_dwordx4 v[10:11], v[2:5], off nt
.LBB0_152:
	s_or_b64 exec, exec, s[12:13]
	ds_read2_b32 v[2:3], v78 offset0:48 offset1:113
	ds_read2_b32 v[4:5], v78 offset0:178 offset1:243
	ds_read2_b32 v[10:11], v8 offset0:52 offset1:117
	ds_read2_b32 v[12:13], v8 offset0:182 offset1:247
	v_or_b32_e32 v9, s0, v84
	v_cmp_gt_i32_e32 vcc, s46, v9
	s_waitcnt lgkmcnt(3)
	v_cvt_pk_bf16_f32 v2, v2, v3
	s_waitcnt lgkmcnt(2)
	v_cvt_pk_bf16_f32 v3, v4, v5
	s_waitcnt lgkmcnt(1)
	v_cvt_pk_bf16_f32 v4, v10, v11
	s_waitcnt lgkmcnt(0)
	v_cvt_pk_bf16_f32 v5, v12, v13
	s_and_saveexec_b64 s[12:13], vcc
	s_cbranch_execz .LBB0_154
	s_lshr_b32 s1, s0, 1
	s_and_b32 s1, s1, 0x60
	v_and_b32_e32 v10, 0xffffff17, v9
	v_or_b32_e32 v10, s1, v10
	v_or_b32_e32 v10, 0x80, v10
	v_cmp_lt_i32_e32 vcc, s48, v9
	s_nop 1
	v_cndmask_b32_e32 v10, v10, v9, vcc
	v_ashrrev_i32_e32 v11, 31, v10
	v_lshlrev_b64 v[10:11], 12, v[10:11]
	v_lshl_add_u64 v[10:11], v[6:7], 0, v[10:11]
	global_store_dwordx4 v[10:11], v[2:5], off nt
.LBB0_154:
	s_or_b64 exec, exec, s[12:13]
	ds_read2_b32 v[2:3], v78 offset0:56 offset1:121
	ds_read2_b32 v[4:5], v78 offset0:186 offset1:251
	ds_read2_b32 v[10:11], v8 offset0:60 offset1:125
	ds_read2_b32 v[8:9], v8 offset0:190 offset1:255
	s_waitcnt lgkmcnt(3)
	v_cvt_pk_bf16_f32 v2, v2, v3
	s_waitcnt lgkmcnt(2)
	v_cvt_pk_bf16_f32 v3, v4, v5
	s_waitcnt lgkmcnt(1)
	v_cvt_pk_bf16_f32 v4, v10, v11
	s_waitcnt lgkmcnt(0)
	v_cvt_pk_bf16_f32 v5, v8, v9
	v_or_b32_e32 v8, s0, v85
	v_cmp_gt_i32_e32 vcc, s46, v8
	s_and_saveexec_b64 s[12:13], vcc
	s_cbranch_execz .LBB0_7
	s_lshr_b32 s0, s0, 1
	s_and_b32 s0, s0, 0x60
	v_and_b32_e32 v9, 0xffffff1f, v8
	v_or_b32_e32 v9, s0, v9
	v_or_b32_e32 v9, 0x80, v9
	v_cmp_lt_i32_e32 vcc, s48, v8
	s_nop 1
	v_cndmask_b32_e32 v8, v9, v8, vcc
	v_ashrrev_i32_e32 v9, 31, v8
	v_lshlrev_b64 v[8:9], 12, v[8:9]
	v_lshl_add_u64 v[6:7], v[6:7], 0, v[8:9]
	global_store_dwordx4 v[6:7], v[2:5], off nt
	s_branch .LBB0_7
